# full-line nt set plus first (static) attention ticket remapped so every XCD starts on its own head (K/V L2 locality)
# baseline (speedup 1.0000x reference)
.LBB0_496:
	v_mul_hi_u32 v2, v6, s12
	v_lshrrev_b32_e32 v10, 8, v2
	v_mul_u32_u24_e32 v2, 0x101, v10
	v_lshl_add_u64 v[8:9], v[2:3], 2, s[4:5]
	global_load_dword v7, v[4:5], off
	v_cmp_lt_u32_e32 vcc, s13, v6
	global_load_dword v8, v[8:9], off offset:1024
	v_add_u32_e32 v9, 0x200, v6
	v_mov_b32_e32 v6, v9
	v_mul_u32_u24_e32 v9, 0x410, v10
	v_lshlrev_b32_e32 v2, 2, v2
	v_sub_u32_e32 v2, v9, v2
	v_lshl_add_u64 v[4:5], v[4:5], 0, s[8:9]
	s_or_b64 s[6:7], vcc, s[6:7]
	v_add_u32_e32 v2, v1, v2
	v_add_u32_e32 v1, 0x800, v1
	s_waitcnt vmcnt(0)
	v_sub_f32_e32 v7, v7, v8
	v_mul_f32_e32 v7, 0x3fb8aa3b, v7
	ds_write_b32 v2, v7
	s_andn2_b64 exec, exec, s[6:7]
	s_cbranch_execnz .LBB0_496
	s_or_b64 exec, exec, s[6:7]
	s_lshl_b32 s4, s65, 3
	s_add_i32 s25, s4, s70
	s_and_b32 s4, s25, 0xff
	s_lshl_b32 s4, s4, 3
	s_lshr_b32 s25, s25, 8
	s_or_b32 s25, s25, s4
	s_cmpk_gt_i32 s25, 0x21ff
	s_waitcnt lgkmcnt(0)
	s_barrier
	s_cbranch_scc1 .LBB0_581
	s_lshl_b32 s4, s2, 8
	s_and_b32 s4, s4, 0x700
	s_add_u32 s16, s52, s4
	s_addc_u32 s17, s53, 0
	s_lshl_b32 s6, s70, 14
	s_add_i32 s63, s6, 0
	s_mov_b32 s36, 0
	v_cmp_eq_u32_e64 s[4:5], 0, v184
	s_and_b32 s62, s2, 7
	v_mov_b32_e32 v3, 0
	v_mov_b32_e32 v1, s63
	s_mov_b32 s64, 0xd900000
	s_mov_b32 s12, 0x3f803f80
	s_mov_b32 s66, 0x41000000
	s_movk_i32 s67, 0x90
	s_mov_b64 s[18:19], 0x8000
	s_mov_b64 s[20:21], 0x10000
	v_bfrev_b32_e32 v18, 1
	v_mov_b32_e32 v185, 0x100
	s_branch .LBB0_501
